# scan compute loop: the 30 packed v_pk_mul_f32 (decay scaling between MFMAs) split into single v_mul_f32 pairs (7.5 packed-vs-scalar rule), bit-identical
# baseline (speedup 1.0000x reference)
.LBB0_1852:
	s_add_u32 s16, s16, 0xe0000
	s_addc_u32 s17, s17, 0
	s_add_u32 s18, s18, 0xe0000
	s_addc_u32 s19, s19, 0
	s_add_i32 s8, s11, 2
	s_cmpk_lt_u32 s11, 0xfe
	s_cselect_b32 s66, s8, 0xff
	s_add_u32 s0, s4, s66
	s_addc_u32 s1, s5, 0
	s_lshl_b64 s[0:1], s[0:1], 14
	s_lshl_b64 s[14:15], s[66:67], 2
	s_add_u32 s14, s12, s14
	v_lshl_add_u64 v[40:41], v[56:57], 0, s[0:1]
	s_addc_u32 s15, s13, s15
	global_load_dwordx2 v[66:67], v[40:41], off
	global_load_dwordx2 v[60:61], v[40:41], off offset:32
	global_load_dwordx2 v[62:63], v[40:41], off offset:64
	global_load_dwordx2 v[64:65], v[40:41], off offset:96
	global_load_dword v79, v161, s[14:15]
	ds_read_b128 v[114:117], v71
	ds_read_b128 v[118:121], v71 offset:4096
	ds_read_b128 v[122:125], v71 offset:16384
	ds_read_b128 v[126:129], v71 offset:20480
	ds_read_b128 v[130:133], v71 offset:8192
	ds_read_b128 v[134:137], v71 offset:12288
	ds_read_b128 v[138:141], v71 offset:24576
	ds_read_b128 v[142:145], v71 offset:28672
	s_min_u32 s0, s11, 0xfc
	s_add_i32 s9, s0, 3
	s_add_u32 s0, s4, s9
	s_addc_u32 s1, s5, 0
	s_lshl_b64 s[0:1], s[0:1], 14
	s_lshl_b32 s10, s9, 2
	s_add_i32 s9, 0, 0x12000
	v_lshl_add_u64 v[202:203], v[56:57], 0, s[0:1]
	v_mov_b32_e32 v204, s10
	global_load_dwordx2 v[238:239], v[202:203], off
	global_load_dwordx2 v[240:241], v[202:203], off offset:32
	global_load_dwordx2 v[242:243], v[202:203], off offset:64
	global_load_dwordx2 v[244:245], v[202:203], off offset:96
	global_load_dword v205, v204, s[12:13]
	v_lshlrev_b32_e32 v106, 16, v36
	v_and_b32_e32 v107, 0xffff0000, v36
	v_lshlrev_b32_e32 v108, 16, v37
	v_and_b32_e32 v109, 0xffff0000, v37
	v_lshlrev_b32_e32 v36, 16, v38
	v_and_b32_e32 v37, 0xffff0000, v38
	v_lshlrev_b32_e32 v38, 16, v39
	v_and_b32_e32 v39, 0xffff0000, v39
	s_cmpk_gt_u32 s11, 0xfd
	v_cvt_pk_bf16_f32 v40, v16, v17
	v_cvt_pk_bf16_f32 v41, v18, v19
	v_cvt_pk_bf16_f32 v42, v8, v9
	v_cvt_pk_bf16_f32 v43, v10, v11
	v_cvt_pk_bf16_f32 v44, v20, v21
	v_cvt_pk_bf16_f32 v45, v22, v23
	v_cvt_pk_bf16_f32 v46, v0, v1
	v_cvt_pk_bf16_f32 v47, v2, v3
	v_cvt_pk_bf16_f32 v48, v24, v25
	v_cvt_pk_bf16_f32 v49, v26, v27
	v_cvt_pk_bf16_f32 v50, v12, v13
	v_cvt_pk_bf16_f32 v51, v14, v15
	v_cvt_pk_bf16_f32 v52, v28, v29
	v_cvt_pk_bf16_f32 v53, v30, v31
	v_cvt_pk_bf16_f32 v54, v4, v5
	v_cvt_pk_bf16_f32 v55, v6, v7
	v_lshlrev_b32_e32 v110, 16, v34
	v_and_b32_e32 v111, 0xffff0000, v34
	v_lshlrev_b32_e32 v112, 16, v35
	v_and_b32_e32 v113, 0xffff0000, v35
	v_lshlrev_b32_e32 v146, 16, v32
	v_and_b32_e32 v147, 0xffff0000, v32
	v_lshlrev_b32_e32 v148, 16, v33
	v_and_b32_e32 v149, 0xffff0000, v33
	ds_read_b128 v[32:35], v83
	ds_read_b128 v[150:153], v83 offset:4096
	ds_read_b128 v[154:157], v83 offset:16384
	ds_read_b128 v[166:169], v83 offset:20480
	ds_read_b128 v[170:173], v83 offset:8192
	ds_read_b128 v[174:177], v83 offset:12288
	ds_read_b128 v[178:181], v83 offset:24576
	ds_read_b128 v[182:185], v83 offset:28672
	s_waitcnt lgkmcnt(8)
	v_mfma_f32_16x16x32_bf16 v[36:39], v[118:121], v[40:43], v[36:39]
	v_mfma_f32_16x16x32_bf16 v[106:109], v[114:117], v[40:43], v[106:109]
	v_mfma_f32_16x16x32_bf16 v[114:117], v[122:125], v[40:43], 0
	v_mfma_f32_16x16x32_bf16 v[118:121], v[126:129], v[40:43], 0
	v_mfma_f32_16x16x32_bf16 v[110:113], v[130:133], v[40:43], v[110:113]
	v_mfma_f32_16x16x32_bf16 v[122:125], v[138:141], v[40:43], 0
	v_mfma_f32_16x16x32_bf16 v[126:129], v[134:137], v[40:43], v[146:149]
	v_mfma_f32_16x16x32_bf16 v[40:43], v[142:145], v[40:43], 0
	ds_read_b128 v[130:133], v87
	ds_read_b128 v[134:137], v87 offset:4096
	ds_read_b128 v[138:141], v87 offset:16384
	ds_read_b128 v[142:145], v87 offset:20480
	ds_read_b128 v[146:149], v87 offset:8192
	ds_read_b128 v[186:189], v87 offset:12288
	ds_read_b128 v[190:193], v87 offset:24576
	ds_read_b128 v[194:197], v87 offset:28672
	s_waitcnt lgkmcnt(8)
	v_mfma_f32_16x16x32_bf16 v[32:35], v[32:35], v[44:47], v[106:109]
	v_mfma_f32_16x16x32_bf16 v[36:39], v[150:153], v[44:47], v[36:39]
	v_mfma_f32_16x16x32_bf16 v[106:109], v[154:157], v[44:47], v[114:117]
	v_mfma_f32_16x16x32_bf16 v[114:117], v[166:169], v[44:47], v[118:121]
	v_mfma_f32_16x16x32_bf16 v[110:113], v[170:173], v[44:47], v[110:113]
	v_mfma_f32_16x16x32_bf16 v[118:121], v[178:181], v[44:47], v[122:125]
	v_mfma_f32_16x16x32_bf16 v[122:125], v[174:177], v[44:47], v[126:129]
	v_mfma_f32_16x16x32_bf16 v[40:43], v[182:185], v[44:47], v[40:43]
	s_nop 1
	ds_read_b128 v[126:129], v91
	ds_read_b128 v[150:153], v91 offset:4096
	ds_read_b128 v[154:157], v91 offset:16384
	ds_read_b128 v[166:169], v91 offset:20480
	ds_read_b128 v[170:173], v91 offset:8192
	ds_read_b128 v[174:177], v91 offset:12288
	ds_read_b128 v[178:181], v91 offset:24576
	ds_read_b128 v[182:185], v91 offset:28672
	s_waitcnt lgkmcnt(8)
	v_mfma_f32_16x16x32_bf16 v[130:133], v[130:133], v[48:51], v[32:35]
	v_mfma_f32_16x16x32_bf16 v[106:109], v[138:141], v[48:51], v[106:109]
	v_mfma_f32_16x16x32_bf16 v[134:137], v[134:137], v[48:51], v[36:39]
	v_mfma_f32_16x16x32_bf16 v[114:117], v[142:145], v[48:51], v[114:117]
	v_mfma_f32_16x16x32_bf16 v[110:113], v[146:149], v[48:51], v[110:113]
	v_mfma_f32_16x16x32_bf16 v[118:121], v[190:193], v[48:51], v[118:121]
	v_mfma_f32_16x16x32_bf16 v[122:125], v[186:189], v[48:51], v[122:125]
	v_mfma_f32_16x16x32_bf16 v[48:51], v[194:197], v[48:51], v[40:43]
	ds_read_b128 v[138:141], v95 offset:32768
	ds_read_b128 v[44:47], v95 offset:34816
	ds_read_b128 v[142:145], v96 offset:32768
	ds_read_b128 v[40:43], v96 offset:34816
	ds_read_b128 v[146:149], v95 offset:36864
	ds_read_b128 v[36:39], v95 offset:38912
	ds_read_b128 v[186:189], v96 offset:36864
	ds_read_b128 v[32:35], v96 offset:38912
	s_waitcnt lgkmcnt(8)
	v_mfma_f32_16x16x32_bf16 v[126:129], v[126:129], v[52:55], v[130:133]
	v_mfma_f32_16x16x32_bf16 v[106:109], v[154:157], v[52:55], v[106:109]
	v_mfma_f32_16x16x32_bf16 v[130:133], v[150:153], v[52:55], v[134:137]
	v_mfma_f32_16x16x32_bf16 v[114:117], v[166:169], v[52:55], v[114:117]
	v_mfma_f32_16x16x32_bf16 v[110:113], v[170:173], v[52:55], v[110:113]
	v_mfma_f32_16x16x32_bf16 v[118:121], v[178:181], v[52:55], v[118:121]
	v_mfma_f32_16x16x32_bf16 v[122:125], v[174:177], v[52:55], v[122:125]
	v_mfma_f32_16x16x32_bf16 v[134:137], v[182:185], v[52:55], v[48:51]
	ds_read_b128 v[154:157], v95 offset:40960
	ds_read_b128 v[166:169], v96 offset:40960
	ds_read_b128 v[170:173], v95 offset:43008
	ds_read_b128 v[174:177], v96 offset:43008
	ds_read_b128 v[178:181], v95 offset:45056
	ds_read_b128 v[182:185], v96 offset:45056
	ds_read_b128 v[48:51], v95 offset:47104
	ds_read_b128 v[52:55], v96 offset:47104
	v_mul_f32_e32 v18, v78, v18
	v_mul_f32_e32 v19, v78, v19
	v_mul_f32_e32 v16, v78, v16
	v_mul_f32_e32 v17, v78, v17
	v_mul_f32_e32 v22, v78, v22
	v_mul_f32_e32 v23, v78, v23
	v_mul_f32_e32 v20, v78, v20
	v_mul_f32_e32 v21, v78, v21
	v_mul_f32_e32 v26, v78, v26
	v_mul_f32_e32 v27, v78, v27
	v_mul_f32_e32 v24, v78, v24
	v_mul_f32_e32 v25, v78, v25
	v_mul_f32_e32 v152, v78, v30
	v_mul_f32_e32 v153, v78, v31
	v_mul_f32_e32 v150, v78, v28
	v_mul_f32_e32 v151, v78, v29
	v_cvt_pk_bf16_f32 v126, v126, v127
	v_cvt_pk_bf16_f32 v127, v128, v129
	v_cvt_pk_bf16_f32 v128, v130, v131
	v_cvt_pk_bf16_f32 v129, v132, v133
	v_cvt_pk_bf16_f32 v110, v110, v111
	v_cvt_pk_bf16_f32 v111, v112, v113
	s_waitcnt lgkmcnt(14)
	v_mfma_f32_16x16x32_bf16 v[16:19], v[138:141], v[126:129], v[16:19]
	v_cvt_pk_bf16_f32 v112, v122, v123
	v_cvt_pk_bf16_f32 v113, v124, v125
	s_waitcnt lgkmcnt(9)
	v_mfma_f32_16x16x32_bf16 v[20:23], v[146:149], v[126:129], v[20:23]
	v_mfma_f32_16x16x32_bf16 v[28:31], v[142:145], v[110:113], v[16:19]
	v_mfma_f32_16x16x32_bf16 v[20:23], v[186:189], v[110:113], v[20:23]
	ds_read_b128 v[122:125], v95 offset:49152
	ds_read_b128 v[130:133], v95 offset:51200
	ds_read_b128 v[138:141], v96 offset:49152
	ds_read_b128 v[142:145], v96 offset:51200
	ds_read_b128 v[146:149], v95 offset:53248
	ds_read_b128 v[186:189], v95 offset:55296
	ds_read_b128 v[190:193], v96 offset:53248
	ds_read_b128 v[194:197], v96 offset:55296
	s_waitcnt lgkmcnt(10)
	v_mfma_f32_16x16x32_bf16 v[16:19], v[154:157], v[126:129], v[24:27]
	v_mfma_f32_16x16x32_bf16 v[150:153], v[178:181], v[126:129], v[150:153]
	v_mfma_f32_16x16x32_bf16 v[24:27], v[166:169], v[110:113], v[16:19]
	v_mfma_f32_16x16x32_bf16 v[16:19], v[182:185], v[110:113], v[150:153]
	s_waitcnt lgkmcnt(7)
	v_mfma_f32_16x16x32_bf16 v[106:109], v[122:125], v[126:129], v[106:109]
	v_mul_f32_e32 v10, v78, v10
	v_mul_f32_e32 v11, v78, v11
	v_mul_f32_e32 v8, v78, v8
	v_mul_f32_e32 v9, v78, v9
	s_waitcnt lgkmcnt(5)
	v_mfma_f32_16x16x32_bf16 v[106:109], v[138:141], v[110:113], v[106:109]
	v_mul_f32_e64 v2, v78, v2
	v_mul_f32_e64 v3, v78, v3
	v_mul_f32_e32 v0, v78, v0
	v_mul_f32_e32 v1, v78, v1
	v_mul_f32_e32 v6, v78, v6
	v_mul_f32_e32 v7, v78, v7
	v_mfma_f32_16x16x32_bf16 v[114:117], v[130:133], v[126:129], v[114:117]
	v_mul_f32_e64 v4, v78, v4
	v_mul_f32_e64 v5, v78, v5
	s_nop 0
	v_cvt_pk_bf16_f32 v105, v106, s0
	s_waitcnt lgkmcnt(3)
	v_mfma_f32_16x16x32_bf16 v[118:121], v[146:149], v[126:129], v[118:121]
	global_store_short v222, v105, s[16:17]
	v_cvt_pk_bf16_f32 v105, v107, s0
	s_waitcnt lgkmcnt(2)
	v_mfma_f32_16x16x32_bf16 v[122:125], v[186:189], v[126:129], v[134:137]
	global_store_short v223, v105, s[16:17]
	v_cvt_pk_bf16_f32 v105, v108, s0
	v_mfma_f32_16x16x32_bf16 v[114:117], v[142:145], v[110:113], v[114:117]
	global_store_short v224, v105, s[16:17]
	v_cvt_pk_bf16_f32 v105, v109, s0
	v_lshlrev_b32_e32 v150, 16, v68
	s_waitcnt lgkmcnt(1)
	v_mfma_f32_16x16x32_bf16 v[106:109], v[190:193], v[110:113], v[118:121]
	v_and_b32_e32 v151, 0xffff0000, v68
	v_lshlrev_b32_e32 v152, 16, v69
	v_and_b32_e32 v153, 0xffff0000, v69
	global_store_short v225, v105, s[16:17]
	s_waitcnt lgkmcnt(0)
	v_mfma_f32_16x16x32_bf16 v[118:121], v[194:197], v[110:113], v[122:125]
	v_cvt_pk_bf16_f32 v105, v114, s0
	global_store_short v226, v105, s[16:17]
	v_cvt_pk_bf16_f32 v105, v115, s0
	global_store_short v227, v105, s[16:17]
	v_cvt_pk_bf16_f32 v105, v116, s0
	global_store_short v228, v105, s[16:17]
	v_cvt_pk_bf16_f32 v105, v117, s0
	global_store_short v229, v105, s[16:17]
	v_cvt_pk_bf16_f32 v105, v106, s0
	global_store_short v230, v105, s[16:17]
	v_cvt_pk_bf16_f32 v105, v107, s0
	global_store_short v231, v105, s[16:17]
	v_cvt_pk_bf16_f32 v105, v108, s0
	global_store_short v232, v105, s[16:17]
	v_cvt_pk_bf16_f32 v105, v109, s0
	global_store_short v233, v105, s[16:17]
	v_cvt_pk_bf16_f32 v105, v118, s0
	global_store_short v234, v105, s[16:17]
	v_mfma_f32_16x16x32_bf16 v[8:11], v[44:47], v[126:129], v[8:11]
	v_cvt_pk_bf16_f32 v105, v119, s0
	global_store_short v235, v105, s[16:17]
	v_cvt_pk_bf16_f32 v105, v120, s0
	v_mfma_f32_16x16x32_bf16 v[40:43], v[40:43], v[110:113], v[8:11]
	global_store_short v236, v105, s[16:17]
	v_cvt_pk_bf16_f32 v44, v121, s0
	v_lshlrev_b32_e32 v114, 16, v72
	s_nop 0
	v_mul_f32_e32 v8, v78, v12
	v_mul_f32_e32 v9, v78, v13
	v_mfma_f32_16x16x32_bf16 v[0:3], v[36:39], v[126:129], v[0:3]
	global_store_short v237, v44, s[16:17]
	s_barrier
	v_mfma_f32_16x16x32_bf16 v[4:7], v[48:51], v[126:129], v[4:7]
	v_mul_f32_e32 v10, v78, v14
	v_mul_f32_e32 v11, v78, v15
	v_mfma_f32_16x16x32_bf16 v[4:7], v[52:55], v[110:113], v[4:7]
	ds_read_b128 v[118:121], v71 offset:57344
	ds_read_b128 v[122:125], v71 offset:61440
	v_cvt_pk_bf16_f32 v12, v28, v29
	v_mfma_f32_16x16x32_bf16 v[8:11], v[170:173], v[126:129], v[8:11]
	ds_read_b128 v[126:129], v206
	ds_read_b128 v[130:133], v206 offset:4096
	ds_read_b128 v[134:137], v81 offset:57344
	ds_read_b128 v[138:141], v206 offset:8192
	v_mfma_f32_16x16x32_bf16 v[0:3], v[32:35], v[110:113], v[0:3]
	ds_read_b128 v[142:145], v82 offset:57344
	ds_read_b128 v[146:149], v206 offset:12288
	v_cvt_pk_bf16_f32 v13, v30, v31
	v_mfma_f32_16x16x32_bf16 v[8:11], v[174:177], v[110:113], v[8:11]
	v_cvt_pk_bf16_f32 v14, v40, v41
	v_cvt_pk_bf16_f32 v15, v42, v43
	v_cvt_pk_bf16_f32 v32, v20, v21
	v_cvt_pk_bf16_f32 v33, v22, v23
	v_cvt_pk_bf16_f32 v34, v0, v1
	v_cvt_pk_bf16_f32 v35, v2, v3
	v_and_b32_e32 v115, 0xffff0000, v72
	v_lshlrev_b32_e32 v116, 16, v73
	v_and_b32_e32 v117, 0xffff0000, v73
	v_lshlrev_b32_e32 v72, 16, v74
	v_and_b32_e32 v73, 0xffff0000, v74
	v_lshlrev_b32_e32 v74, 16, v75
	v_and_b32_e32 v75, 0xffff0000, v75
	v_cvt_pk_bf16_f32 v50, v24, v25
	v_cvt_pk_bf16_f32 v51, v26, v27
	v_cvt_pk_bf16_f32 v52, v8, v9
	v_cvt_pk_bf16_f32 v53, v10, v11
	v_cvt_pk_bf16_f32 v106, v16, v17
	v_cvt_pk_bf16_f32 v107, v18, v19
	v_cvt_pk_bf16_f32 v108, v4, v5
	v_cvt_pk_bf16_f32 v109, v6, v7
	v_lshlrev_b32_e32 v110, 16, v76
	v_and_b32_e32 v111, 0xffff0000, v76
	v_lshlrev_b32_e32 v112, 16, v77
	v_and_b32_e32 v113, 0xffff0000, v77
	ds_read_b128 v[154:157], v83 offset:57344
	ds_read_b128 v[166:169], v83 offset:61440
	ds_read_b128 v[170:173], v207
	ds_read_b128 v[174:177], v207 offset:4096
	ds_read_b128 v[178:181], v85 offset:57344
	ds_read_b128 v[182:185], v207 offset:8192
	ds_read_b128 v[186:189], v86 offset:57344
	ds_read_b128 v[190:193], v207 offset:12288
	s_waitcnt lgkmcnt(8)
	v_mfma_f32_16x16x32_bf16 v[110:113], v[118:121], v[12:15], v[110:113]
	v_mfma_f32_16x16x32_bf16 v[118:121], v[126:129], v[12:15], 0
	v_mfma_f32_16x16x32_bf16 v[114:117], v[122:125], v[12:15], v[114:117]
	v_mfma_f32_16x16x32_bf16 v[122:125], v[130:133], v[12:15], 0
	v_mfma_f32_16x16x32_bf16 v[72:75], v[134:137], v[12:15], v[72:75]
	v_mfma_f32_16x16x32_bf16 v[126:129], v[138:141], v[12:15], 0
	v_mfma_f32_16x16x32_bf16 v[130:133], v[142:145], v[12:15], v[150:153]
	v_mfma_f32_16x16x32_bf16 v[12:15], v[146:149], v[12:15], 0
	ds_read_b128 v[134:137], v87 offset:57344
	ds_read_b128 v[102:105], v87 offset:61440
	ds_read_b128 v[138:141], v249
	ds_read_b128 v[142:145], v249 offset:4096
	ds_read_b128 v[146:149], v89 offset:57344
	ds_read_b128 v[150:153], v249 offset:8192
	ds_read_b128 v[194:197], v90 offset:57344
	ds_read_b128 v[198:201], v249 offset:12288
	s_waitcnt lgkmcnt(8)
	v_mfma_f32_16x16x32_bf16 v[72:75], v[178:181], v[32:35], v[72:75]
	v_mfma_f32_16x16x32_bf16 v[12:15], v[190:193], v[32:35], v[12:15]
	v_mfma_f32_16x16x32_bf16 v[110:113], v[154:157], v[32:35], v[110:113]
	v_mfma_f32_16x16x32_bf16 v[118:121], v[170:173], v[32:35], v[118:121]
	v_mfma_f32_16x16x32_bf16 v[114:117], v[166:169], v[32:35], v[114:117]
	v_mfma_f32_16x16x32_bf16 v[122:125], v[174:177], v[32:35], v[122:125]
	v_mfma_f32_16x16x32_bf16 v[126:129], v[182:185], v[32:35], v[126:129]
	v_mfma_f32_16x16x32_bf16 v[130:133], v[186:189], v[32:35], v[130:133]
	ds_read_b128 v[32:35], v91 offset:57344
	ds_read_b128 v[154:157], v91 offset:61440
	ds_read_b128 v[166:169], v250
	ds_read_b128 v[170:173], v250 offset:4096
	ds_read_b128 v[174:177], v93 offset:57344
	ds_read_b128 v[178:181], v250 offset:8192
	ds_read_b128 v[182:185], v94 offset:57344
	ds_read_b128 v[186:189], v250 offset:12288
	s_waitcnt lgkmcnt(8)
	v_mfma_f32_16x16x32_bf16 v[72:75], v[146:149], v[50:53], v[72:75]
	v_mfma_f32_16x16x32_bf16 v[12:15], v[198:201], v[50:53], v[12:15]
	v_mfma_f32_16x16x32_bf16 v[110:113], v[134:137], v[50:53], v[110:113]
	v_mfma_f32_16x16x32_bf16 v[118:121], v[138:141], v[50:53], v[118:121]
	v_mfma_f32_16x16x32_bf16 v[102:105], v[102:105], v[50:53], v[114:117]
	v_mfma_f32_16x16x32_bf16 v[114:117], v[142:145], v[50:53], v[122:125]
	v_mfma_f32_16x16x32_bf16 v[122:125], v[150:153], v[50:53], v[126:129]
	v_mfma_f32_16x16x32_bf16 v[126:129], v[194:197], v[50:53], v[130:133]
	ds_read_b128 v[50:53], v97
	s_nop 1
	ds_read_b128 v[130:133], v97 offset:2048
	ds_read_b128 v[134:137], v98
	ds_read_b128 v[138:141], v98 offset:2048
	ds_read_b128 v[142:145], v97 offset:4096
	ds_read_b128 v[146:149], v97 offset:6144
	ds_read_b128 v[150:153], v98 offset:4096
	ds_read_b128 v[190:193], v98 offset:6144
	s_waitcnt lgkmcnt(8)
	v_mfma_f32_16x16x32_bf16 v[32:35], v[32:35], v[106:109], v[110:113]
	v_mfma_f32_16x16x32_bf16 v[72:75], v[174:177], v[106:109], v[72:75]
	v_mfma_f32_16x16x32_bf16 v[110:113], v[166:169], v[106:109], v[118:121]
	v_mfma_f32_16x16x32_bf16 v[102:105], v[154:157], v[106:109], v[102:105]
	v_mfma_f32_16x16x32_bf16 v[114:117], v[170:173], v[106:109], v[114:117]
	v_mfma_f32_16x16x32_bf16 v[118:121], v[178:181], v[106:109], v[122:125]
	v_mfma_f32_16x16x32_bf16 v[122:125], v[182:185], v[106:109], v[126:129]
	v_mfma_f32_16x16x32_bf16 v[106:109], v[186:189], v[106:109], v[12:15]
	ds_read_b128 v[154:157], v97 offset:8192
	ds_read_b128 v[166:169], v98 offset:8192
	ds_read_b128 v[170:173], v97 offset:10240
	ds_read_b128 v[174:177], v98 offset:10240
	ds_read_b128 v[178:181], v97 offset:12288
	ds_read_b128 v[182:185], v98 offset:12288
	ds_read_b128 v[186:189], v97 offset:14336
	ds_read_b128 v[194:197], v98 offset:14336
	v_mul_f32_e32 v14, v70, v30
	v_mul_f32_e32 v15, v70, v31
	v_mul_f32_e32 v12, v70, v28
	v_mul_f32_e32 v13, v70, v29
	v_mul_f32_e32 v30, v70, v42
	v_mul_f32_e32 v31, v70, v43
	v_mul_f32_e32 v28, v70, v40
	v_mul_f32_e32 v29, v70, v41
	v_mul_f32_e32 v22, v70, v22
	v_mul_f32_e32 v23, v70, v23
	v_mul_f32_e32 v20, v70, v20
	v_mul_f32_e32 v21, v70, v21
	v_mul_f32_e32 v2, v70, v2
	v_mul_f32_e32 v3, v70, v3
	v_mul_f32_e32 v0, v70, v0
	v_mul_f32_e32 v1, v70, v1
	v_mul_f32_e32 v26, v70, v26
	v_mul_f32_e32 v27, v70, v27
	v_mul_f32_e32 v24, v70, v24
	v_mul_f32_e32 v25, v70, v25
	v_mul_f32_e32 v6, v70, v6
	v_mul_f32_e32 v7, v70, v7
	v_mul_f32_e32 v4, v70, v4
	v_mul_f32_e32 v5, v70, v5
	v_mul_f32_e32 v42, v70, v10
	v_mul_f32_e32 v43, v70, v11
	v_mul_f32_e32 v40, v70, v8
	v_mul_f32_e32 v41, v70, v9
	v_mul_f32_e32 v128, v70, v18
	v_mul_f32_e32 v129, v70, v19
	v_mul_f32_e32 v126, v70, v16
	v_mul_f32_e32 v127, v70, v17
	v_cvt_pk_bf16_f32 v32, v32, v33
	v_cvt_pk_bf16_f32 v33, v34, v35
	v_cvt_pk_bf16_f32 v34, v102, v103
	v_cvt_pk_bf16_f32 v35, v104, v105
	s_waitcnt lgkmcnt(14)
	s_nop 0
	v_mfma_f32_16x16x32_bf16 v[8:11], v[50:53], v[32:35], v[12:15]
	v_cvt_pk_bf16_f32 v50, v72, v73
	v_cvt_pk_bf16_f32 v51, v74, v75
	v_cvt_pk_bf16_f32 v52, v122, v123
	v_mfma_f32_16x16x32_bf16 v[12:15], v[130:133], v[32:35], v[28:31]
	v_cvt_pk_bf16_f32 v53, v124, v125
	s_waitcnt lgkmcnt(8)
	v_mfma_f32_16x16x32_bf16 v[20:23], v[142:145], v[32:35], v[20:23]
	v_mfma_f32_16x16x32_bf16 v[0:3], v[146:149], v[32:35], v[0:3]
	v_mfma_f32_16x16x32_bf16 v[16:19], v[134:137], v[50:53], v[8:11]
	v_mfma_f32_16x16x32_bf16 v[8:11], v[138:141], v[50:53], v[12:15]
	v_mfma_f32_16x16x32_bf16 v[20:23], v[150:153], v[50:53], v[20:23]
	v_mfma_f32_16x16x32_bf16 v[0:3], v[190:193], v[50:53], v[0:3]
	ds_read_b128 v[72:75], v99
	ds_read_b128 v[102:105], v99 offset:2048
	ds_read_b128 v[122:125], v100
	ds_read_b128 v[130:133], v100 offset:2048
	ds_read_b128 v[134:137], v99 offset:4096
	ds_read_b128 v[138:141], v99 offset:6144
	ds_read_b128 v[142:145], v100 offset:4096
	ds_read_b128 v[146:149], v100 offset:6144
	s_waitcnt lgkmcnt(8)
	v_mfma_f32_16x16x32_bf16 v[12:15], v[154:157], v[32:35], v[24:27]
	v_mfma_f32_16x16x32_bf16 v[28:31], v[170:173], v[32:35], v[40:43]
	v_mfma_f32_16x16x32_bf16 v[40:43], v[178:181], v[32:35], v[126:129]
	v_mfma_f32_16x16x32_bf16 v[4:7], v[186:189], v[32:35], v[4:7]
	v_mfma_f32_16x16x32_bf16 v[24:27], v[166:169], v[50:53], v[12:15]
	v_mfma_f32_16x16x32_bf16 v[12:15], v[174:177], v[50:53], v[28:31]
	v_mfma_f32_16x16x32_bf16 v[28:31], v[182:185], v[50:53], v[40:43]
	v_mfma_f32_16x16x32_bf16 v[4:7], v[194:197], v[50:53], v[4:7]
	s_waitcnt lgkmcnt(7)
	v_mfma_f32_16x16x32_bf16 v[40:43], v[72:75], v[32:35], v[110:113]
	s_waitcnt vmcnt(16)
	v_mov_b64_e32 v[76:77], v[238:239]
	v_mov_b64_e32 v[68:69], v[244:245]
	v_mov_b64_e32 v[38:39], v[60:61]
	s_waitcnt lgkmcnt(5)
	v_mfma_f32_16x16x32_bf16 v[40:43], v[122:125], v[50:53], v[40:43]
	s_mov_b32 s11, s8
	v_mov_b32_e32 v78, v79
	v_mov_b32_e32 v70, v205
	v_mfma_f32_16x16x32_bf16 v[72:75], v[102:105], v[32:35], v[114:117]
	s_waitcnt lgkmcnt(3)
	v_mfma_f32_16x16x32_bf16 v[102:105], v[134:137], v[32:35], v[118:121]
	s_nop 1
	v_cvt_pk_bf16_f32 v40, v40, s0
	v_cvt_pk_bf16_f32 v49, v41, s0
	s_waitcnt lgkmcnt(0)
	v_mfma_f32_16x16x32_bf16 v[32:35], v[138:141], v[32:35], v[106:109]
	v_mfma_f32_16x16x32_bf16 v[72:75], v[130:133], v[50:53], v[72:75]
	v_mfma_f32_16x16x32_bf16 v[102:105], v[142:145], v[50:53], v[102:105]
	v_mfma_f32_16x16x32_bf16 v[32:35], v[146:149], v[50:53], v[32:35]
	global_store_short v222, v40, s[18:19]
	v_cvt_pk_bf16_f32 v42, v42, s0
	global_store_short v223, v49, s[18:19]
	global_store_short v224, v42, s[18:19]
	v_cvt_pk_bf16_f32 v42, v43, s0
	global_store_short v225, v42, s[18:19]
	v_cvt_pk_bf16_f32 v42, v72, s0
	global_store_short v226, v42, s[18:19]
	v_cvt_pk_bf16_f32 v42, v73, s0
	v_mov_b64_e32 v[72:73], v[240:241]
	global_store_short v227, v42, s[18:19]
	v_cvt_pk_bf16_f32 v42, v74, s0
	global_store_short v228, v42, s[18:19]
	v_cvt_pk_bf16_f32 v42, v75, s0
	v_mov_b64_e32 v[74:75], v[242:243]
	global_store_short v229, v42, s[18:19]
	v_cvt_pk_bf16_f32 v42, v102, s0
	v_mov_b64_e32 v[36:37], v[66:67]
	global_store_short v230, v42, s[18:19]
	v_cvt_pk_bf16_f32 v42, v103, s0
	global_store_short v231, v42, s[18:19]
	v_cvt_pk_bf16_f32 v42, v104, s0
	global_store_short v232, v42, s[18:19]
	v_cvt_pk_bf16_f32 v42, v105, s0
	v_cvt_pk_bf16_f32 v32, v32, s0
	global_store_short v233, v42, s[18:19]
	global_store_short v234, v32, s[18:19]
	v_cvt_pk_bf16_f32 v40, v33, s0
	v_cvt_pk_bf16_f32 v34, v34, s0
	global_store_short v235, v40, s[18:19]
	global_store_short v236, v34, s[18:19]
	v_cvt_pk_bf16_f32 v34, v35, s0
	global_store_short v237, v34, s[18:19]
	v_mov_b64_e32 v[34:35], v[62:63]
	v_mov_b64_e32 v[32:33], v[64:65]
	s_barrier
	s_cbranch_scc0 .LBB0_1852
